# tail-row YN normalize assigned to workgroups 64+ (those with two tail tiles); otherwise as previous version
# speedup vs baseline: 1.0303x; 1.0057x over previous
; __device__ __forceinline__ KP kparams() { KP p = (KP)__builtin_amdgcn_kernarg_segment_ptr(); asm volatile("" : "+s"(p)); return p; }
; __device__ __forceinline__ void yn_normalize(const Ctx& C_) {
;     const Ctx C = get_ids(C_.wave);
;     KP kp = kparams(); unsigned char* ws = kp->ws; (void)ws;
;     bf16_t* const L_YN = (bf16_t*)(ws + WS_YN);
;     float* const L_SSQ = (float*)(ws + WS_SSQ);
;     const int gw = C.bid * NWAVES + C.wave, NGW = C.G * NWAVES, lane = C.lane;
;     for (int m = gw; m < MREAL; m += NGW) {
;         const f32x4* sp = (const f32x4*)(L_SSQ + (size_t)m * 32);
.LBB0_813:
	s_or_b64 exec, exec, s[2:3]
	s_waitcnt lgkmcnt(0)
	v_mov_b32_e32 v1, v174
	s_mov_b32 s1, s75
	s_mov_b32 s0, s74
	s_mov_b32 s4, s70
	s_barrier
	s_lshl_b32 s4, s4, 3
	v_readlane_b32 s2, v255, 3
	s_add_i32 s8, s4, s1
	s_addk_i32 s8, 0x3e00
	v_readlane_b32 s3, v255, 4
	s_cmpk_lt_i32 s8, 0x4000
	s_cbranch_scc1 .LBB0_816
	s_cmpk_gt_i32 s8, 0x447f
	s_cbranch_scc1 .LBB0_816
	s_load_dwordx2 s[10:11], s[2:3], 0xd8
	s_lshl_b32 s12, s0, 3
	v_lshlrev_b32_e32 v2, 3, v1
	s_ashr_i32 s9, s8, 31
	v_ashrrev_i32_e32 v3, 31, v2
	s_lshl_b64 s[0:1], s[8:9], 12
	s_ashr_i32 s13, s12, 31
	v_lshl_add_u64 v[2:3], v[2:3], 1, s[0:1]
	s_lshl_b64 s[14:15], s[12:13], 12
	s_lshl_b64 s[16:17], s[8:9], 7
	s_lshl_b64 s[18:19], s[12:13], 7
	s_mov_b32 s20, 0x3b000000
